# P8/P9 made independent (last 12 m-tiles of first-half H parked in unused second half of d_out) and the grid barrier between them removed
# speedup vs baseline: 1.0097x; 1.0097x over previous
; DI unsigned pk2(float lo, float hi) { f32x2_t v = {lo, hi}; bf16x2_t b = __builtin_convertvector(v, bf16x2_t); return __builtin_bit_cast(unsigned, b); }
; DI float sigmoidf_(float x) { return 1.0f / (1.0f + __expf(-x)); }
;     DI void operator()(AccRef acc, const Unit& u, int wr, int wc, int fr, int fq) const {
;         const int row0 = u.pm * BM + wr * 64 + fr, col0 = u.pn * 128 + wc * 32 + 8 * fq;
; #pragma unroll
;         for (int ai = 0; ai < 2; ++ai)
; #pragma unroll
;             for (int m = 0; m < 4; ++m) {
;                 const int row = row0 + ai * HALF + m * 16; const float rs = rsqrtf(SS1[row] * (1.0f / DM) + EPSN);
;                 float h[8];
; #pragma unroll
;                 for (int n = 0; n < 2; ++n)
; #pragma unroll
;                     for (int e = 0; e < 4; ++e) { const float g = acc[ai][0][m][n][e] * rs, up = acc[ai][1][m][n][e] * rs; h[4 * n + e] = g * sigmoidf_(g) * up; }
;                 u32x4 w; w.x = pk2(h[0], h[1]); w.y = pk2(h[2], h[3]); w.z = pk2(h[4], h[5]); w.w = pk2(h[6], h[7]);
;                 *(u32x4*)(H + (size_t)row * DFF + col0) = w;
;             }
.LBB0_1490:
	v_lshl_add_u32 v144, s0, 8, v149
	v_ashrrev_i32_e32 v145, 31, v144
	v_lshl_add_u64 v[146:147], v[144:145], 2, s[46:47]
	global_load_dword v145, v[146:147], off
	global_load_dword v248, v[146:147], off offset:64
	global_load_dword v249, v[146:147], off offset:128
	global_load_dword v250, v[146:147], off offset:192
	global_load_dword v251, v[146:147], off offset:512
	global_load_dword v252, v[146:147], off offset:576
	global_load_dword v253, v[146:147], off offset:640
	global_load_dword v254, v[146:147], off offset:704
	s_waitcnt vmcnt(0)
	v_fmamk_f32 v145, v145, 0x3a800000, v158
	v_mul_f32_e32 v152, 0x4b800000, v145
	v_cmp_gt_f32_e32 vcc, s43, v145
	s_nop 1
	v_cndmask_b32_e32 v145, v145, v152, vcc
	v_rsq_f32_e32 v145, v145
	v_lshl_or_b32 v152, s1, 7, v154
	v_ashrrev_i32_e32 v153, 31, v152
	v_mul_f32_e32 v159, 0x45800000, v145
	v_cndmask_b32_e32 v160, v145, v159, vcc
	v_pk_mul_f32 v[124:125], v[124:125], v[160:161] op_sel_hi:[1,0]
	v_pk_mul_f32 v[126:127], v[126:127], v[160:161] op_sel_hi:[1,0]
	v_mul_f32_e32 v145, 0xbfb8aa3b, v124
	v_mul_f32_e32 v159, 0xbfb8aa3b, v125
	v_exp_f32_e32 v162, v145
	v_exp_f32_e32 v163, v159
	v_pk_mul_f32 v[120:121], v[120:121], v[160:161] op_sel_hi:[1,0]
	v_pk_mul_f32 v[122:123], v[122:123], v[160:161] op_sel_hi:[1,0]
	v_pk_mul_f32 v[116:117], v[116:117], v[160:161] op_sel_hi:[1,0]
	v_mul_f32_e32 v161, 0xbfb8aa3b, v126
	v_mul_f32_e32 v165, 0xbfb8aa3b, v127
	v_exp_f32_e32 v164, v161
	v_exp_f32_e32 v165, v165
	v_pk_add_f32 v[162:163], v[162:163], 1.0 op_sel_hi:[1,0]
	v_pk_mul_f32 v[112:113], v[112:113], v[160:161] op_sel_hi:[1,0]
	v_pk_add_f32 v[164:165], v[164:165], 1.0 op_sel_hi:[1,0]
	v_mul_f32_e32 v166, 0xbfb8aa3b, v116
	v_mul_f32_e32 v167, 0xbfb8aa3b, v117
	v_exp_f32_e32 v166, v166
	v_exp_f32_e32 v167, v167
	s_nop 0
	v_pk_add_f32 v[166:167], v[166:167], 1.0 op_sel_hi:[1,0]
	v_rcp_f32_e32 v163, v163
	v_rcp_f32_e32 v162, v162
	s_nop 0
	v_pk_mul_f32 v[124:125], v[124:125], v[162:163]
	v_rcp_f32_e32 v163, v165
	v_rcp_f32_e32 v162, v164
	v_pk_mul_f32 v[120:121], v[120:121], v[124:125]
	v_pk_mul_f32 v[124:125], v[126:127], v[162:163]
	v_pk_mul_f32 v[118:119], v[118:119], v[160:161] op_sel_hi:[1,0]
	v_pk_mul_f32 v[122:123], v[122:123], v[124:125]
	v_mul_f32_e32 v124, 0xbfb8aa3b, v118
	v_mul_f32_e32 v125, 0xbfb8aa3b, v119
	v_exp_f32_e32 v124, v124
	v_exp_f32_e32 v125, v125
	s_nop 0
	v_pk_add_f32 v[124:125], v[124:125], 1.0 op_sel_hi:[1,0]
	v_rcp_f32_e32 v127, v167
	v_rcp_f32_e32 v126, v166
	s_nop 0
	v_pk_mul_f32 v[116:117], v[116:117], v[126:127]
	v_pk_mul_f32 v[114:115], v[114:115], v[160:161] op_sel_hi:[1,0]
	v_pk_mul_f32 v[112:113], v[112:113], v[116:117]
	v_rcp_f32_e32 v117, v125
	v_rcp_f32_e32 v116, v124
	s_nop 0
	v_pk_mul_f32 v[116:117], v[118:119], v[116:117]
	v_cvt_pk_bf16_f32 v118, v112, v113
	v_pk_mul_f32 v[114:115], v[114:115], v[116:117]
	s_sub_i32 s98, s0, 52
	s_cmp_lt_u32 s98, 12
	s_cbranch_scc1 .Lp7_hb_alt
	s_cmp_gt_i32 s0, 63
	s_cselect_b32 s98, 0x1000000, 0
	s_sub_u32 s98, s48, s98
	s_subb_u32 s99, s49, 0
	s_branch .Lp7_hb_done
	s_nop 0
	s_nop 0
	s_nop 0
	s_nop 0
	s_nop 0
	s_nop 0
	s_nop 0
	s_nop 0
	s_nop 0
.Lp7_hb_alt:
	s_sub_u32 s98, s80, 0x780000
	s_subb_u32 s99, s81, 0
.Lp7_hb_done:
	v_mov_b64_e32 v[112:113], s[98:99]
	v_cvt_pk_bf16_f32 v116, v120, v121
	v_cvt_pk_bf16_f32 v119, v114, v115
	v_mad_i64_i32 v[120:121], s[0:1], v144, s44, v[112:113]
	v_lshlrev_b64 v[114:115], 1, v[152:153]
	v_cvt_pk_bf16_f32 v117, v122, v123
	v_lshl_add_u64 v[120:121], v[120:121], 0, v[114:115]
	global_store_dwordx4 v[120:121], v[116:119], off
	s_nop 1
	v_or_b32_e32 v116, 16, v144
	v_ashrrev_i32_e32 v117, 31, v116
	v_lshl_add_u64 v[118:119], v[116:117], 2, s[46:47]
	s_nop 0
	s_nop 0
	v_fmamk_f32 v117, v248, 0x3a800000, v158
	v_mul_f32_e32 v118, 0x4b800000, v117
	v_cmp_gt_f32_e32 vcc, s43, v117
	s_nop 1
	v_cndmask_b32_e32 v117, v117, v118, vcc
	v_rsq_f32_e32 v117, v117
	s_nop 0
	v_mul_f32_e32 v118, 0x45800000, v117
	v_cndmask_b32_e32 v118, v117, v118, vcc
	v_pk_mul_f32 v[108:109], v[108:109], v[118:119] op_sel_hi:[1,0]
	v_pk_mul_f32 v[110:111], v[110:111], v[118:119] op_sel_hi:[1,0]
	v_mul_f32_e32 v117, 0xbfb8aa3b, v108
	v_mul_f32_e32 v119, 0xbfb8aa3b, v109
	v_exp_f32_e32 v120, v117
	v_exp_f32_e32 v121, v119
	v_mul_f32_e32 v122, 0xbfb8aa3b, v110
	v_mul_f32_e32 v123, 0xbfb8aa3b, v111
	v_exp_f32_e32 v122, v122
	v_pk_add_f32 v[120:121], v[120:121], 1.0 op_sel_hi:[1,0]
	v_exp_f32_e32 v123, v123
	s_nop 0
	v_pk_add_f32 v[122:123], v[122:123], 1.0 op_sel_hi:[1,0]
	v_pk_mul_f32 v[104:105], v[104:105], v[118:119] op_sel_hi:[1,0]
	v_pk_mul_f32 v[106:107], v[106:107], v[118:119] op_sel_hi:[1,0]
	v_rcp_f32_e32 v121, v121
	v_rcp_f32_e32 v120, v120
	s_nop 0
	v_pk_mul_f32 v[108:109], v[108:109], v[120:121]
	v_pk_mul_f32 v[104:105], v[104:105], v[108:109]
	v_rcp_f32_e32 v109, v123
	v_pk_mul_f32 v[100:101], v[100:101], v[118:119] op_sel_hi:[1,0]
	v_mul_f32_e32 v117, 0xbfb8aa3b, v100
	v_exp_f32_e32 v120, v117
	v_mul_f32_e32 v117, 0xbfb8aa3b, v101
	v_exp_f32_e32 v121, v117
	v_rcp_f32_e32 v108, v122
	s_nop 0
	v_pk_mul_f32 v[108:109], v[110:111], v[108:109]
	v_pk_add_f32 v[120:121], v[120:121], 1.0 op_sel_hi:[1,0]
	v_pk_mul_f32 v[106:107], v[106:107], v[108:109]
	s_nop 0
	v_pk_mul_f32 v[96:97], v[96:97], v[118:119] op_sel_hi:[1,0]
	v_rcp_f32_e32 v109, v121
	v_pk_mul_f32 v[102:103], v[102:103], v[118:119] op_sel_hi:[1,0]
	v_mul_f32_e32 v110, 0xbfb8aa3b, v102
	v_mul_f32_e32 v111, 0xbfb8aa3b, v103
	v_exp_f32_e32 v110, v110
	v_exp_f32_e32 v111, v111
	v_rcp_f32_e32 v108, v120
	s_nop 0
	v_pk_mul_f32 v[100:101], v[100:101], v[108:109]
	v_pk_add_f32 v[110:111], v[110:111], 1.0 op_sel_hi:[1,0]
	v_pk_mul_f32 v[100:101], v[96:97], v[100:101]
; DI unsigned pk2(float lo, float hi) { f32x2_t v = {lo, hi}; bf16x2_t b = __builtin_convertvector(v, bf16x2_t); return __builtin_bit_cast(unsigned, b); }
; DI float sigmoidf_(float x) { return 1.0f / (1.0f + __expf(-x)); }
;     DI void operator()(AccRef acc, const Unit& u, int wr, int wc, int fr, int fq) const {
;     ...
;         for (int ai = 0; ai < 2; ++ai)
; #pragma unroll
;             for (int m = 0; m < 4; ++m) {
;                 const int row = row0 + ai * HALF + m * 16; const float rs = rsqrtf(SS1[row] * (1.0f / DM) + EPSN);
;                 float h[8];
; #pragma unroll
;                 for (int n = 0; n < 2; ++n)
; #pragma unroll
;                     for (int e = 0; e < 4; ++e) { const float g = acc[ai][0][m][n][e] * rs, up = acc[ai][1][m][n][e] * rs; h[4 * n + e] = g * sigmoidf_(g) * up; }
;                 u32x4 w; w.x = pk2(h[0], h[1]); w.y = pk2(h[2], h[3]); w.z = pk2(h[4], h[5]); w.w = pk2(h[6], h[7]);
;                 *(u32x4*)(H + (size_t)row * DFF + col0) = w;
;             }
	s_nop 0
	v_pk_mul_f32 v[96:97], v[98:99], v[118:119] op_sel_hi:[1,0]
	v_rcp_f32_e32 v99, v111
	v_rcp_f32_e32 v98, v110
	s_nop 0
	v_pk_mul_f32 v[98:99], v[102:103], v[98:99]
	s_nop 0
	v_pk_mul_f32 v[102:103], v[96:97], v[98:99]
	v_cvt_pk_bf16_f32 v98, v100, v101
	v_mad_i64_i32 v[100:101], s[0:1], v116, s44, v[112:113]
	v_cvt_pk_bf16_f32 v96, v104, v105
	v_cvt_pk_bf16_f32 v97, v106, v107
	v_cvt_pk_bf16_f32 v99, v102, v103
	v_lshl_add_u64 v[100:101], v[100:101], 0, v[114:115]
	global_store_dwordx4 v[100:101], v[96:99], off
	s_nop 1
	v_or_b32_e32 v96, 32, v144
	v_ashrrev_i32_e32 v97, 31, v96
	v_lshl_add_u64 v[98:99], v[96:97], 2, s[46:47]
	s_nop 0
	s_nop 0
	v_fmamk_f32 v97, v249, 0x3a800000, v158
	v_mul_f32_e32 v98, 0x4b800000, v97
	v_cmp_gt_f32_e32 vcc, s43, v97
	s_nop 1
	v_cndmask_b32_e32 v97, v97, v98, vcc
	v_rsq_f32_e32 v97, v97
	s_nop 0
	v_mul_f32_e32 v98, 0x45800000, v97
	v_cndmask_b32_e32 v98, v97, v98, vcc
	v_pk_mul_f32 v[92:93], v[92:93], v[98:99] op_sel_hi:[1,0]
	s_nop 0
	v_mul_f32_e32 v97, 0xbfb8aa3b, v92
	v_exp_f32_e32 v100, v97
	v_mul_f32_e32 v97, 0xbfb8aa3b, v93
	v_exp_f32_e32 v101, v97
	s_nop 0
	v_pk_add_f32 v[100:101], v[100:101], 1.0 op_sel_hi:[1,0]
	s_nop 0
	s_nop 0
	v_pk_mul_f32 v[88:89], v[88:89], v[98:99] op_sel_hi:[1,0]
	v_rcp_f32_e32 v101, v101
	v_pk_mul_f32 v[94:95], v[94:95], v[98:99] op_sel_hi:[1,0]
	v_mul_f32_e32 v102, 0xbfb8aa3b, v94
	v_mul_f32_e32 v103, 0xbfb8aa3b, v95
	v_exp_f32_e32 v102, v102
	v_exp_f32_e32 v103, v103
	v_rcp_f32_e32 v100, v100
	s_nop 0
	v_pk_mul_f32 v[92:93], v[92:93], v[100:101]
	v_pk_add_f32 v[102:103], v[102:103], 1.0 op_sel_hi:[1,0]
	v_pk_mul_f32 v[88:89], v[88:89], v[92:93]
	s_nop 0
	v_pk_mul_f32 v[90:91], v[90:91], v[98:99] op_sel_hi:[1,0]
	v_rcp_f32_e32 v93, v103
	v_pk_mul_f32 v[84:85], v[84:85], v[98:99] op_sel_hi:[1,0]
	v_mul_f32_e32 v97, 0xbfb8aa3b, v84
	v_exp_f32_e32 v100, v97
	v_mul_f32_e32 v97, 0xbfb8aa3b, v85
	v_exp_f32_e32 v101, v97
	v_rcp_f32_e32 v92, v102
	s_nop 0
	v_pk_mul_f32 v[92:93], v[94:95], v[92:93]
	v_pk_add_f32 v[100:101], v[100:101], 1.0 op_sel_hi:[1,0]
	v_pk_mul_f32 v[90:91], v[90:91], v[92:93]
	s_nop 0
	v_pk_mul_f32 v[80:81], v[80:81], v[98:99] op_sel_hi:[1,0]
	v_rcp_f32_e32 v93, v101
	v_pk_mul_f32 v[86:87], v[86:87], v[98:99] op_sel_hi:[1,0]
	v_mul_f32_e32 v94, 0xbfb8aa3b, v86
	v_mul_f32_e32 v95, 0xbfb8aa3b, v87
	v_exp_f32_e32 v94, v94
	v_exp_f32_e32 v95, v95
	v_rcp_f32_e32 v92, v100
	s_nop 0
	v_pk_mul_f32 v[84:85], v[84:85], v[92:93]
	v_pk_add_f32 v[94:95], v[94:95], 1.0 op_sel_hi:[1,0]
	v_pk_mul_f32 v[84:85], v[80:81], v[84:85]
	s_nop 0
	v_pk_mul_f32 v[80:81], v[82:83], v[98:99] op_sel_hi:[1,0]
	v_rcp_f32_e32 v83, v95
	v_rcp_f32_e32 v82, v94
	s_nop 0
	v_pk_mul_f32 v[82:83], v[86:87], v[82:83]
	s_nop 0
	v_pk_mul_f32 v[86:87], v[80:81], v[82:83]
	v_cvt_pk_bf16_f32 v82, v84, v85
	v_mad_i64_i32 v[84:85], s[0:1], v96, s44, v[112:113]
	v_cvt_pk_bf16_f32 v80, v88, v89
	v_cvt_pk_bf16_f32 v81, v90, v91
	v_cvt_pk_bf16_f32 v83, v86, v87
	v_lshl_add_u64 v[84:85], v[84:85], 0, v[114:115]
	global_store_dwordx4 v[84:85], v[80:83], off
	s_nop 1
	v_or_b32_e32 v80, 48, v144
	v_ashrrev_i32_e32 v81, 31, v80
	v_lshl_add_u64 v[82:83], v[80:81], 2, s[46:47]
	s_nop 0
	s_nop 0
	v_fmamk_f32 v81, v250, 0x3a800000, v158
	v_mul_f32_e32 v82, 0x4b800000, v81
	v_cmp_gt_f32_e32 vcc, s43, v81
	s_nop 1
	v_cndmask_b32_e32 v81, v81, v82, vcc
	v_rsq_f32_e32 v81, v81
	s_nop 0
	v_mul_f32_e32 v82, 0x45800000, v81
	v_cndmask_b32_e32 v82, v81, v82, vcc
	v_pk_mul_f32 v[76:77], v[76:77], v[82:83] op_sel_hi:[1,0]
	s_nop 0
	v_mul_f32_e32 v81, 0xbfb8aa3b, v76
	v_exp_f32_e32 v84, v81
	v_mul_f32_e32 v81, 0xbfb8aa3b, v77
	v_exp_f32_e32 v85, v81
	s_nop 0
	v_pk_add_f32 v[84:85], v[84:85], 1.0 op_sel_hi:[1,0]
	s_nop 0
	s_nop 0
	v_pk_mul_f32 v[72:73], v[72:73], v[82:83] op_sel_hi:[1,0]
	v_rcp_f32_e32 v85, v85
	v_pk_mul_f32 v[78:79], v[78:79], v[82:83] op_sel_hi:[1,0]
	v_mul_f32_e32 v86, 0xbfb8aa3b, v78
	v_mul_f32_e32 v87, 0xbfb8aa3b, v79
	v_exp_f32_e32 v86, v86
	v_exp_f32_e32 v87, v87
	v_rcp_f32_e32 v84, v84
	s_nop 0
	v_pk_mul_f32 v[76:77], v[76:77], v[84:85]
	v_pk_add_f32 v[86:87], v[86:87], 1.0 op_sel_hi:[1,0]
	v_pk_mul_f32 v[72:73], v[72:73], v[76:77]
	s_nop 0
	v_pk_mul_f32 v[74:75], v[74:75], v[82:83] op_sel_hi:[1,0]
	v_rcp_f32_e32 v77, v87
	v_pk_mul_f32 v[68:69], v[68:69], v[82:83] op_sel_hi:[1,0]
	v_mul_f32_e32 v81, 0xbfb8aa3b, v68
	v_exp_f32_e32 v84, v81
	v_mul_f32_e32 v81, 0xbfb8aa3b, v69
	v_exp_f32_e32 v85, v81
	v_rcp_f32_e32 v76, v86
	s_nop 0
	v_pk_mul_f32 v[76:77], v[78:79], v[76:77]
	v_pk_add_f32 v[84:85], v[84:85], 1.0 op_sel_hi:[1,0]
	v_pk_mul_f32 v[74:75], v[74:75], v[76:77]
	s_nop 0
	v_pk_mul_f32 v[64:65], v[64:65], v[82:83] op_sel_hi:[1,0]
	v_rcp_f32_e32 v77, v85
	v_pk_mul_f32 v[70:71], v[70:71], v[82:83] op_sel_hi:[1,0]
	v_mul_f32_e32 v78, 0xbfb8aa3b, v70
	v_mul_f32_e32 v79, 0xbfb8aa3b, v71
	v_exp_f32_e32 v78, v78
	v_exp_f32_e32 v79, v79
	v_rcp_f32_e32 v76, v84
	s_nop 0
	v_pk_mul_f32 v[68:69], v[68:69], v[76:77]
	v_pk_add_f32 v[78:79], v[78:79], 1.0 op_sel_hi:[1,0]
	v_pk_mul_f32 v[68:69], v[64:65], v[68:69]
	s_nop 0
	v_pk_mul_f32 v[64:65], v[66:67], v[82:83] op_sel_hi:[1,0]
	v_rcp_f32_e32 v67, v79
	v_rcp_f32_e32 v66, v78
	s_nop 0
	v_pk_mul_f32 v[66:67], v[70:71], v[66:67]
	s_nop 0
	v_pk_mul_f32 v[70:71], v[64:65], v[66:67]
	v_cvt_pk_bf16_f32 v66, v68, v69
	v_mad_i64_i32 v[68:69], s[0:1], v80, s44, v[112:113]
	v_cvt_pk_bf16_f32 v64, v72, v73
	v_cvt_pk_bf16_f32 v65, v74, v75
	v_cvt_pk_bf16_f32 v67, v70, v71
	v_lshl_add_u64 v[68:69], v[68:69], 0, v[114:115]
	global_store_dwordx4 v[68:69], v[64:67], off
	s_nop 0
	v_add_u32_e32 v70, 0x80, v144
	s_nop 0
	v_fmamk_f32 v64, v251, 0x3a800000, v158
; DI unsigned pk2(float lo, float hi) { f32x2_t v = {lo, hi}; bf16x2_t b = __builtin_convertvector(v, bf16x2_t); return __builtin_bit_cast(unsigned, b); }
; DI float sigmoidf_(float x) { return 1.0f / (1.0f + __expf(-x)); }
;     DI void operator()(AccRef acc, const Unit& u, int wr, int wc, int fr, int fq) const {
;     ...
;         for (int ai = 0; ai < 2; ++ai)
; #pragma unroll
;             for (int m = 0; m < 4; ++m) {
;                 const int row = row0 + ai * HALF + m * 16; const float rs = rsqrtf(SS1[row] * (1.0f / DM) + EPSN);
;                 float h[8];
; #pragma unroll
;                 for (int n = 0; n < 2; ++n)
; #pragma unroll
;                     for (int e = 0; e < 4; ++e) { const float g = acc[ai][0][m][n][e] * rs, up = acc[ai][1][m][n][e] * rs; h[4 * n + e] = g * sigmoidf_(g) * up; }
;                 u32x4 w; w.x = pk2(h[0], h[1]); w.y = pk2(h[2], h[3]); w.z = pk2(h[4], h[5]); w.w = pk2(h[6], h[7]);
;                 *(u32x4*)(H + (size_t)row * DFF + col0) = w;
;             }
	v_mul_f32_e32 v65, 0x4b800000, v64
	v_cmp_gt_f32_e32 vcc, s43, v64
	s_nop 1
	v_cndmask_b32_e32 v64, v64, v65, vcc
	v_rsq_f32_e32 v64, v64
	s_nop 0
	v_mul_f32_e32 v65, 0x45800000, v64
	v_cndmask_b32_e32 v64, v64, v65, vcc
	v_pk_mul_f32 v[60:61], v[60:61], v[64:65] op_sel_hi:[1,0]
	s_nop 0
	v_mul_f32_e32 v65, 0xbfb8aa3b, v60
	v_exp_f32_e32 v66, v65
	v_mul_f32_e32 v65, 0xbfb8aa3b, v61
	v_exp_f32_e32 v67, v65
	s_nop 0
	v_pk_add_f32 v[66:67], v[66:67], 1.0 op_sel_hi:[1,0]
	s_nop 0
	v_pk_mul_f32 v[56:57], v[56:57], v[64:65] op_sel_hi:[1,0]
	v_rcp_f32_e32 v67, v67
	v_pk_mul_f32 v[62:63], v[62:63], v[64:65] op_sel_hi:[1,0]
	v_mul_f32_e32 v68, 0xbfb8aa3b, v62
	v_mul_f32_e32 v69, 0xbfb8aa3b, v63
	v_exp_f32_e32 v68, v68
	v_exp_f32_e32 v69, v69
	v_rcp_f32_e32 v66, v66
	s_nop 0
	v_pk_mul_f32 v[60:61], v[60:61], v[66:67]
	v_pk_add_f32 v[68:69], v[68:69], 1.0 op_sel_hi:[1,0]
	s_nop 0
	v_pk_mul_f32 v[56:57], v[56:57], v[60:61]
	v_pk_mul_f32 v[58:59], v[58:59], v[64:65] op_sel_hi:[1,0]
	v_rcp_f32_e32 v61, v69
	v_pk_mul_f32 v[52:53], v[52:53], v[64:65] op_sel_hi:[1,0]
	v_mul_f32_e32 v65, 0xbfb8aa3b, v52
	v_exp_f32_e32 v66, v65
	v_mul_f32_e32 v65, 0xbfb8aa3b, v53
	v_exp_f32_e32 v67, v65
	v_rcp_f32_e32 v60, v68
	s_nop 0
	v_pk_mul_f32 v[60:61], v[62:63], v[60:61]
	v_pk_add_f32 v[66:67], v[66:67], 1.0 op_sel_hi:[1,0]
	v_pk_mul_f32 v[58:59], v[58:59], v[60:61]
	v_pk_mul_f32 v[48:49], v[48:49], v[64:65] op_sel_hi:[1,0]
	v_rcp_f32_e32 v61, v67
	v_pk_mul_f32 v[54:55], v[54:55], v[64:65] op_sel_hi:[1,0]
	v_mul_f32_e32 v62, 0xbfb8aa3b, v54
	v_mul_f32_e32 v63, 0xbfb8aa3b, v55
	v_exp_f32_e32 v62, v62
	v_exp_f32_e32 v63, v63
	v_rcp_f32_e32 v60, v66
	s_nop 0
	v_pk_mul_f32 v[52:53], v[52:53], v[60:61]
	v_pk_add_f32 v[62:63], v[62:63], 1.0 op_sel_hi:[1,0]
	v_pk_mul_f32 v[52:53], v[48:49], v[52:53]
	v_pk_mul_f32 v[48:49], v[50:51], v[64:65] op_sel_hi:[1,0]
	v_rcp_f32_e32 v51, v63
	v_rcp_f32_e32 v50, v62
	s_nop 0
	v_pk_mul_f32 v[50:51], v[54:55], v[50:51]
	s_nop 0
	v_pk_mul_f32 v[54:55], v[48:49], v[50:51]
	v_cvt_pk_bf16_f32 v50, v52, v53
	v_mad_i64_i32 v[52:53], s[0:1], v70, s44, v[112:113]
	v_cvt_pk_bf16_f32 v48, v56, v57
	v_cvt_pk_bf16_f32 v49, v58, v59
	v_cvt_pk_bf16_f32 v51, v54, v55
	v_lshl_add_u64 v[52:53], v[52:53], 0, v[114:115]
	global_store_dwordx4 v[52:53], v[48:51], off
	s_nop 0
	v_add_u32_e32 v54, 0x90, v144
	s_nop 0
	v_fmamk_f32 v48, v252, 0x3a800000, v158
	v_mul_f32_e32 v49, 0x4b800000, v48
	v_cmp_gt_f32_e32 vcc, s43, v48
	s_nop 1
	v_cndmask_b32_e32 v48, v48, v49, vcc
	v_rsq_f32_e32 v48, v48
	s_nop 0
	v_mul_f32_e32 v49, 0x45800000, v48
	v_cndmask_b32_e32 v48, v48, v49, vcc
	v_pk_mul_f32 v[44:45], v[44:45], v[48:49] op_sel_hi:[1,0]
	s_nop 0
	v_mul_f32_e32 v49, 0xbfb8aa3b, v44
	v_exp_f32_e32 v50, v49
	v_mul_f32_e32 v49, 0xbfb8aa3b, v45
	v_exp_f32_e32 v51, v49
	s_nop 0
	v_pk_add_f32 v[50:51], v[50:51], 1.0 op_sel_hi:[1,0]
	s_nop 0
	v_pk_mul_f32 v[40:41], v[40:41], v[48:49] op_sel_hi:[1,0]
	v_rcp_f32_e32 v51, v51
	v_pk_mul_f32 v[46:47], v[46:47], v[48:49] op_sel_hi:[1,0]
	v_mul_f32_e32 v52, 0xbfb8aa3b, v46
	v_mul_f32_e32 v53, 0xbfb8aa3b, v47
	v_exp_f32_e32 v52, v52
	v_exp_f32_e32 v53, v53
	v_rcp_f32_e32 v50, v50
	s_nop 0
	v_pk_mul_f32 v[44:45], v[44:45], v[50:51]
	v_pk_add_f32 v[52:53], v[52:53], 1.0 op_sel_hi:[1,0]
	s_nop 0
	v_pk_mul_f32 v[40:41], v[40:41], v[44:45]
	v_pk_mul_f32 v[42:43], v[42:43], v[48:49] op_sel_hi:[1,0]
	v_rcp_f32_e32 v45, v53
	v_pk_mul_f32 v[36:37], v[36:37], v[48:49] op_sel_hi:[1,0]
	v_mul_f32_e32 v49, 0xbfb8aa3b, v36
	v_exp_f32_e32 v50, v49
	v_mul_f32_e32 v49, 0xbfb8aa3b, v37
	v_exp_f32_e32 v51, v49
	v_rcp_f32_e32 v44, v52
	s_nop 0
	v_pk_mul_f32 v[44:45], v[46:47], v[44:45]
	v_pk_add_f32 v[50:51], v[50:51], 1.0 op_sel_hi:[1,0]
	v_pk_mul_f32 v[42:43], v[42:43], v[44:45]
	v_pk_mul_f32 v[32:33], v[32:33], v[48:49] op_sel_hi:[1,0]
	v_rcp_f32_e32 v45, v51
	v_pk_mul_f32 v[38:39], v[38:39], v[48:49] op_sel_hi:[1,0]
	v_mul_f32_e32 v46, 0xbfb8aa3b, v38
	v_mul_f32_e32 v47, 0xbfb8aa3b, v39
	v_exp_f32_e32 v46, v46
	v_exp_f32_e32 v47, v47
	v_rcp_f32_e32 v44, v50
	s_nop 0
	v_pk_mul_f32 v[36:37], v[36:37], v[44:45]
	v_pk_add_f32 v[46:47], v[46:47], 1.0 op_sel_hi:[1,0]
	v_pk_mul_f32 v[36:37], v[32:33], v[36:37]
	v_pk_mul_f32 v[32:33], v[34:35], v[48:49] op_sel_hi:[1,0]
	v_rcp_f32_e32 v35, v47
	v_rcp_f32_e32 v34, v46
	s_nop 0
	v_pk_mul_f32 v[34:35], v[38:39], v[34:35]
	s_nop 0
	v_pk_mul_f32 v[38:39], v[32:33], v[34:35]
	v_cvt_pk_bf16_f32 v34, v36, v37
	v_mad_i64_i32 v[36:37], s[0:1], v54, s44, v[112:113]
	v_cvt_pk_bf16_f32 v32, v40, v41
	v_cvt_pk_bf16_f32 v33, v42, v43
	v_cvt_pk_bf16_f32 v35, v38, v39
	v_lshl_add_u64 v[36:37], v[36:37], 0, v[114:115]
	global_store_dwordx4 v[36:37], v[32:35], off
	s_nop 0
	v_add_u32_e32 v38, 0xa0, v144
	s_nop 0
	v_fmamk_f32 v32, v253, 0x3a800000, v158
; DI unsigned pk2(float lo, float hi) { f32x2_t v = {lo, hi}; bf16x2_t b = __builtin_convertvector(v, bf16x2_t); return __builtin_bit_cast(unsigned, b); }
; DI float sigmoidf_(float x) { return 1.0f / (1.0f + __expf(-x)); }
;     DI void operator()(AccRef acc, const Unit& u, int wr, int wc, int fr, int fq) const {
;     ...
;         for (int ai = 0; ai < 2; ++ai)
; #pragma unroll
;             for (int m = 0; m < 4; ++m) {
;                 const int row = row0 + ai * HALF + m * 16; const float rs = rsqrtf(SS1[row] * (1.0f / DM) + EPSN);
;                 float h[8];
; #pragma unroll
;                 for (int n = 0; n < 2; ++n)
; #pragma unroll
;                     for (int e = 0; e < 4; ++e) { const float g = acc[ai][0][m][n][e] * rs, up = acc[ai][1][m][n][e] * rs; h[4 * n + e] = g * sigmoidf_(g) * up; }
;                 u32x4 w; w.x = pk2(h[0], h[1]); w.y = pk2(h[2], h[3]); w.z = pk2(h[4], h[5]); w.w = pk2(h[6], h[7]);
;                 *(u32x4*)(H + (size_t)row * DFF + col0) = w;
;             }
	v_mul_f32_e32 v33, 0x4b800000, v32
	v_cmp_gt_f32_e32 vcc, s43, v32
	s_nop 1
	v_cndmask_b32_e32 v32, v32, v33, vcc
	v_rsq_f32_e32 v32, v32
	s_nop 0
	v_mul_f32_e32 v33, 0x45800000, v32
	v_cndmask_b32_e32 v32, v32, v33, vcc
	v_pk_mul_f32 v[28:29], v[28:29], v[32:33] op_sel_hi:[1,0]
	s_nop 0
	v_mul_f32_e32 v33, 0xbfb8aa3b, v28
	v_exp_f32_e32 v34, v33
	v_mul_f32_e32 v33, 0xbfb8aa3b, v29
	v_exp_f32_e32 v35, v33
	s_nop 0
	v_pk_add_f32 v[34:35], v[34:35], 1.0 op_sel_hi:[1,0]
	s_nop 0
	v_pk_mul_f32 v[24:25], v[24:25], v[32:33] op_sel_hi:[1,0]
	v_rcp_f32_e32 v35, v35
	v_pk_mul_f32 v[30:31], v[30:31], v[32:33] op_sel_hi:[1,0]
	v_mul_f32_e32 v36, 0xbfb8aa3b, v30
	v_mul_f32_e32 v37, 0xbfb8aa3b, v31
	v_exp_f32_e32 v36, v36
	v_exp_f32_e32 v37, v37
	v_rcp_f32_e32 v34, v34
	s_nop 0
	v_pk_mul_f32 v[28:29], v[28:29], v[34:35]
	v_pk_add_f32 v[36:37], v[36:37], 1.0 op_sel_hi:[1,0]
	s_nop 0
	v_pk_mul_f32 v[24:25], v[24:25], v[28:29]
	v_pk_mul_f32 v[26:27], v[26:27], v[32:33] op_sel_hi:[1,0]
	v_rcp_f32_e32 v29, v37
	v_pk_mul_f32 v[20:21], v[20:21], v[32:33] op_sel_hi:[1,0]
	v_mul_f32_e32 v33, 0xbfb8aa3b, v20
	v_exp_f32_e32 v34, v33
	v_mul_f32_e32 v33, 0xbfb8aa3b, v21
	v_exp_f32_e32 v35, v33
	v_rcp_f32_e32 v28, v36
	s_nop 0
	v_pk_mul_f32 v[28:29], v[30:31], v[28:29]
	v_pk_add_f32 v[34:35], v[34:35], 1.0 op_sel_hi:[1,0]
	v_pk_mul_f32 v[26:27], v[26:27], v[28:29]
	v_pk_mul_f32 v[16:17], v[16:17], v[32:33] op_sel_hi:[1,0]
	v_rcp_f32_e32 v29, v35
	v_pk_mul_f32 v[22:23], v[22:23], v[32:33] op_sel_hi:[1,0]
	v_mul_f32_e32 v30, 0xbfb8aa3b, v22
	v_mul_f32_e32 v31, 0xbfb8aa3b, v23
	v_exp_f32_e32 v30, v30
	v_exp_f32_e32 v31, v31
	v_rcp_f32_e32 v28, v34
	s_nop 0
	v_pk_mul_f32 v[20:21], v[20:21], v[28:29]
	v_pk_add_f32 v[30:31], v[30:31], 1.0 op_sel_hi:[1,0]
	v_pk_mul_f32 v[20:21], v[16:17], v[20:21]
	v_pk_mul_f32 v[16:17], v[18:19], v[32:33] op_sel_hi:[1,0]
	v_rcp_f32_e32 v19, v31
	v_rcp_f32_e32 v18, v30
	s_nop 0
	v_pk_mul_f32 v[18:19], v[22:23], v[18:19]
	s_nop 0
	v_pk_mul_f32 v[22:23], v[16:17], v[18:19]
	v_cvt_pk_bf16_f32 v18, v20, v21
	v_mad_i64_i32 v[20:21], s[0:1], v38, s44, v[112:113]
	v_cvt_pk_bf16_f32 v16, v24, v25
	v_cvt_pk_bf16_f32 v17, v26, v27
	v_cvt_pk_bf16_f32 v19, v22, v23
	v_lshl_add_u64 v[20:21], v[20:21], 0, v[114:115]
	global_store_dwordx4 v[20:21], v[16:19], off
	s_nop 0
	v_add_u32_e32 v22, 0xb0, v144
	s_nop 0
	v_fmamk_f32 v16, v254, 0x3a800000, v158
	v_mul_f32_e32 v17, 0x4b800000, v16
	v_cmp_gt_f32_e32 vcc, s43, v16
	s_nop 1
	v_cndmask_b32_e32 v16, v16, v17, vcc
	v_rsq_f32_e32 v16, v16
	s_nop 0
	v_mul_f32_e32 v17, 0x45800000, v16
	v_cndmask_b32_e32 v16, v16, v17, vcc
	v_pk_mul_f32 v[12:13], v[12:13], v[16:17] op_sel_hi:[1,0]
	s_nop 0
	v_mul_f32_e32 v17, 0xbfb8aa3b, v12
	v_exp_f32_e32 v18, v17
	v_mul_f32_e32 v17, 0xbfb8aa3b, v13
	v_exp_f32_e32 v19, v17
	s_nop 0
	v_pk_add_f32 v[18:19], v[18:19], 1.0 op_sel_hi:[1,0]
	s_nop 0
	v_pk_mul_f32 v[8:9], v[8:9], v[16:17] op_sel_hi:[1,0]
	v_rcp_f32_e32 v19, v19
	v_pk_mul_f32 v[14:15], v[14:15], v[16:17] op_sel_hi:[1,0]
	v_mul_f32_e32 v20, 0xbfb8aa3b, v14
	v_mul_f32_e32 v21, 0xbfb8aa3b, v15
	v_exp_f32_e32 v20, v20
	v_exp_f32_e32 v21, v21
	v_rcp_f32_e32 v18, v18
	s_nop 0
	v_pk_mul_f32 v[12:13], v[12:13], v[18:19]
	v_pk_add_f32 v[20:21], v[20:21], 1.0 op_sel_hi:[1,0]
	s_nop 0
	v_pk_mul_f32 v[8:9], v[8:9], v[12:13]
	v_pk_mul_f32 v[10:11], v[10:11], v[16:17] op_sel_hi:[1,0]
	v_rcp_f32_e32 v13, v21
	v_pk_mul_f32 v[4:5], v[4:5], v[16:17] op_sel_hi:[1,0]
	v_mul_f32_e32 v17, 0xbfb8aa3b, v4
	v_exp_f32_e32 v18, v17
	v_mul_f32_e32 v17, 0xbfb8aa3b, v5
	v_exp_f32_e32 v19, v17
	v_rcp_f32_e32 v12, v20
	s_nop 0
	v_pk_mul_f32 v[12:13], v[14:15], v[12:13]
	v_pk_add_f32 v[18:19], v[18:19], 1.0 op_sel_hi:[1,0]
	v_pk_mul_f32 v[10:11], v[10:11], v[12:13]
	v_pk_mul_f32 v[0:1], v[0:1], v[16:17] op_sel_hi:[1,0]
	v_rcp_f32_e32 v13, v19
	v_pk_mul_f32 v[6:7], v[6:7], v[16:17] op_sel_hi:[1,0]
	v_mul_f32_e32 v14, 0xbfb8aa3b, v6
	v_mul_f32_e32 v15, 0xbfb8aa3b, v7
	v_exp_f32_e32 v14, v14
	v_exp_f32_e32 v15, v15
	v_rcp_f32_e32 v12, v18
	s_nop 0
	v_pk_mul_f32 v[4:5], v[4:5], v[12:13]
	v_pk_add_f32 v[14:15], v[14:15], 1.0 op_sel_hi:[1,0]
	v_pk_mul_f32 v[4:5], v[0:1], v[4:5]
	v_pk_mul_f32 v[0:1], v[2:3], v[16:17] op_sel_hi:[1,0]
	v_rcp_f32_e32 v3, v15
	v_rcp_f32_e32 v2, v14
	s_nop 0
	v_pk_mul_f32 v[2:3], v[6:7], v[2:3]
	s_andn2_b64 vcc, exec, s[2:3]
	v_pk_mul_f32 v[6:7], v[0:1], v[2:3]
	v_cvt_pk_bf16_f32 v2, v4, v5
	v_mad_i64_i32 v[4:5], s[0:1], v22, s44, v[112:113]
	v_cvt_pk_bf16_f32 v0, v8, v9
	v_cvt_pk_bf16_f32 v1, v10, v11
	v_cvt_pk_bf16_f32 v3, v6, v7
	v_lshl_add_u64 v[4:5], v[4:5], 0, v[114:115]
	s_mov_b64 s[0:1], -1
	global_store_dwordx4 v[4:5], v[0:3], off
	s_cbranch_vccnz .LBB0_1483
	s_andn2_b64 vcc, exec, s[14:15]
	s_cbranch_vccnz .LBB0_1482
	s_barrier
	s_branch .LBB0_1482

; #define PG8_STAGE(bufoff, gbase, voff) do { _Pragma("unroll") for (int _i = 0; _i < 2; ++_i) \
;         __builtin_amdgcn_global_load_lds((const unsigned*)((const char*)(gbase) + (voff)[_i]), (PG8_LAS unsigned*)(lds + (bufoff) + ldsw + _i * 8192), 16, 0, 0); } while (0)
; #define PG8_WAIT_V(n) asm volatile("s_waitcnt vmcnt(" #n ")" ::: "memory")
; #define PG8_BAR __builtin_amdgcn_s_barrier()
; template <class Epi, class Sched, bool ALIGN_EPI = false, bool SP2 = false>
; __device__ __forceinline__ void gemm_phase(PG8_LAS unsigned char* lds, const Gemm g, const Sched& S, const Epi& E) {
;     ...
;     const char* cA = (const char*)g.A + (size_t)cur.pm * tstep; const char* cB = (const char*)g.Bt + (size_t)cur.pn * tstep;
;     S.a_ready(cur);
;     if constexpr (SP2) {
;         PG8_STAGE(PG8_SB(0, 0), cB, voffB); PG8_STAGE(PG8_SB(0, 1), cB + hstep, voffB); PG8_STAGE(PG8_SA(0, 0), cA, voffA); PG8_STAGE(PG8_SA(0, 1), cA + hstep, voffA);
;         if (wr == 1) PG8_BAR;
;         PG8_WAIT_V(2); PG8_BAR;
;         PG8_STAGE(PG8_SB(1, 0), cB + kstep, voffB); PG8_STAGE(PG8_SA(1, 0), cA + kstep, voffA); PG8_STAGE(PG8_SB(1, 1), cB + hstep + kstep, voffB);
;         PG8_WAIT_V(6); PG8_BAR;
.LBB0_1555:
	s_andn2_b64 vcc, exec, s[0:1]
	s_cbranch_vccnz .LBB0_1602
	v_lshlrev_b32_e32 v0, 4, v150
	s_waitcnt lgkmcnt(0)
	v_and_b32_e32 v1, 32, v150
	v_bfe_u32 v2, v150, 2, 4
	v_bitop3_b32 v8, v0, v1, 48 bitop3:0x6c
	v_lshrrev_b32_e32 v3, 3, v150
	s_movk_i32 s1, 0x70
	v_add_u32_e32 v0, 0x2000, v0
	v_and_or_b32 v3, v3, s1, v2
	v_lshrrev_b32_e32 v0, 7, v0
	s_movk_i32 s1, 0xf0
	v_and_or_b32 v0, v0, s1, v2
	s_lshr_b32 s1, s4, 6
	s_lshr_b32 s0, s4, 8
	s_lshl_b32 s26, s1, 10
	s_mul_i32 s3, s44, 0x160000
	v_and_b32_e32 v9, 64, v150
	s_mul_hi_i32 s2, s44, 0x160000
	s_add_u32 s22, s64, s3
	v_or_b32_e32 v1, v8, v9
	v_mul_u32_u24_e32 v10, 0x1600, v3
	s_addc_u32 s23, s65, s2
	s_add_i32 s27, s26, 0
	v_or_b32_e32 v128, v10, v1
	s_add_i32 m0, s27, 0x10000
	v_mul_u32_u24_e32 v11, 0x1600, v0
	global_load_lds_dwordx4 v128, s[22:23]
	s_add_i32 m0, s27, 0x12000
	v_or_b32_e32 v130, v11, v1
	s_add_u32 s2, s22, 0xb0000
	global_load_lds_dwordx4 v130, s[22:23]
	s_addc_u32 s3, s23, 0
	s_add_i32 m0, s27, 0x14000
	s_mul_i32 s6, s43, 0x160000
	global_load_lds_dwordx4 v128, s[2:3]
	s_add_i32 m0, s27, 0x16000
	s_mul_hi_i32 s5, s43, 0x160000
	s_add_u32 s20, s48, s6
	s_addc_u32 s21, s49, s5
	s_cmp_gt_i32 s43, 51
	s_cbranch_scc0 .Lp8_a0_done
	s_add_u32 s20, s80, s6
	s_addc_u32 s21, s81, s5
	s_sub_u32 s20, s20, 0x780000
	s_subb_u32 s21, s21, 0
.Lp8_a0_done:
	s_add_i32 s28, s27, 0x2000
	global_load_lds_dwordx4 v130, s[2:3]
	s_mov_b32 m0, s27
	s_add_u32 s2, s20, 0xb0000
	global_load_lds_dwordx4 v128, s[20:21]
	s_mov_b32 m0, s28
	s_addc_u32 s3, s21, 0
	s_add_i32 s29, s27, 0x4000
	global_load_lds_dwordx4 v130, s[20:21]
	s_mov_b32 m0, s29
	s_add_i32 s30, s27, 0x6000
	global_load_lds_dwordx4 v128, s[2:3]
	s_mov_b32 m0, s30
	v_mov_b32_e32 v129, 0
	global_load_lds_dwordx4 v130, s[2:3]
	v_mov_b32_e32 v131, v129
	s_cmp_eq_u32 s0, 1
	s_mov_b32 s31, 0
	v_lshl_add_u64 v[6:7], s[22:23], 0, v[128:129]
	v_lshl_add_u64 v[4:5], s[22:23], 0, v[130:131]
	v_lshl_add_u64 v[0:1], s[20:21], 0, v[128:129]
	s_cselect_b64 s[10:11], -1, 0
	s_cmp_lg_u32 s0, 1
	v_lshl_add_u64 v[2:3], s[20:21], 0, v[130:131]
	s_cbranch_scc1 .LBB0_1558
	s_barrier

; template <class Epi, class Sched, bool ALIGN_EPI = false, bool SP2 = false>
; __device__ __forceinline__ void gemm_phase(PG8_LAS unsigned char* lds, const Gemm g, const Sched& S, const Epi& E) {
;     ...
;         const bool has_next = S.next(ui + 1, nxt);
;         const char* nA = has_next ? (const char*)g.A + (size_t)nxt.pm * tstep : cA; const char* nB = has_next ? (const char*)g.Bt + (size_t)nxt.pn * tstep : cB;
.LBB0_1567:
	s_nop 0
	v_cndmask_b32_e64 v0, 0, 1, s[0:1]
	v_cmp_ne_u32_e64 s[6:7], 1, v0
	s_andn2_b64 vcc, exec, s[0:1]
	s_mov_b64 s[0:1], s[20:21]
	s_cbranch_vccnz .LBB0_1569
	s_mul_i32 s0, s42, 0x160000
	s_mul_hi_i32 s1, s42, 0x160000
	s_add_u32 s0, s48, s0
	s_addc_u32 s1, s49, s1
	s_cmp_gt_i32 s42, 51
	s_cbranch_scc0 .LBB0_1569
	s_sub_u32 s0, s0, s48
	s_subb_u32 s1, s1, s49
	s_add_u32 s0, s0, s80
	s_addc_u32 s1, s1, s81
	s_sub_u32 s0, s0, 0x780000
	s_subb_u32 s1, s1, 0

; __device__ __forceinline__ unsigned xb_add(unsigned* p, unsigned v) { return __hip_atomic_fetch_add(p, v, __ATOMIC_RELAXED, __HIP_MEMORY_SCOPE_AGENT); }
; __device__ __forceinline__ void xcd_barrier(const XcdBarrier& b) {
;     asm volatile("s_waitcnt vmcnt(0)" ::: "memory");
;     __syncthreads();
;     if (threadIdx.x == 0) {
;         unsigned* bar = b.bar;
;         __builtin_amdgcn_s_waitcnt(0);
;         unsigned nloc = b.st[0], nx = b.st[1];
;         if (nloc == 0u) { xcd_barrier_complete(bar, b.x, nloc, nx); b.st[0] = nloc; b.st[1] = nx; }
;         const unsigned old = xb_add(&bar[XB_XSUB(b.x)], 1u);
.LBB0_1602:
	s_cmp_gt_i32 s85, 9
	s_cselect_b64 s[0:1], -1, 0
	s_and_b64 s[2:3], s[8:9], s[0:1]
	s_andn2_b64 vcc, exec, s[2:3]
	s_branch .LBB0_1656
	s_waitcnt vmcnt(0)
	s_waitcnt lgkmcnt(0)
	s_barrier
	s_mov_b64 s[2:3], exec
	v_readlane_b32 s4, v246, 0
	v_readlane_b32 s5, v246, 1
	s_and_b64 s[4:5], s[2:3], s[4:5]
	s_mov_b64 exec, s[4:5]
	s_cbranch_execz .LBB0_1655
	s_add_i32 s4, 0, 0x23fc0
	v_mov_b32_e32 v0, s4
	s_waitcnt vmcnt(0) expcnt(0) lgkmcnt(0)
	ds_read_b32 v2, v0
	s_add_i32 s4, 0, 0x23fc4
	v_mov_b32_e32 v0, s4
	ds_read_b32 v0, v0
	s_waitcnt lgkmcnt(1)
	v_cmp_ne_u32_e32 vcc, 0, v2
	s_cbranch_vccnz .LBB0_1619
	s_load_dwordx2 s[8:9], s[96:97], 0x4
	s_add_u32 s4, s82, 0x80200
	s_addc_u32 s5, s83, 0
	s_add_u32 s6, s82, 0x80400
	s_addc_u32 s7, s83, 0
	s_waitcnt lgkmcnt(0)
	s_mul_i32 s50, s8, s89
	s_add_u32 s8, s82, 0x80500
	s_mul_i32 s50, s50, s9
	s_addc_u32 s9, s83, 0
	s_add_u32 s10, s82, 0x80600
	s_addc_u32 s11, s83, 0
	s_add_u32 s14, s82, 0x80700
	s_addc_u32 s15, s83, 0
	s_add_u32 s16, s82, 0x80800
	s_addc_u32 s17, s83, 0
	s_add_u32 s18, s82, 0x80900
	s_addc_u32 s19, s83, 0
	s_add_u32 s20, s82, 0x80a00
	s_addc_u32 s21, s83, 0
	s_add_u32 s22, s82, 0x80b00
	s_addc_u32 s23, s83, 0
	s_add_u32 s24, s82, 0x80c00
	s_addc_u32 s25, s83, 0
	s_add_u32 s26, s82, 0x80d00
	s_addc_u32 s27, s83, 0
	s_add_u32 s28, s82, 0x80e00
	s_addc_u32 s29, s83, 0
	s_add_u32 s30, s82, 0x80f00
	s_addc_u32 s31, s83, 0
	s_add_u32 s34, s82, 0x81000
	s_addc_u32 s35, s83, 0
	s_add_u32 s36, s82, 0x81100
	s_addc_u32 s37, s83, 0
	s_add_u32 s38, s82, 0x81200
	s_addc_u32 s39, s83, 0
	s_add_u32 s40, s82, 0x81300
	s_addc_u32 s41, s83, 0
	s_mov_b32 s51, 1
	v_mov_b32_e32 v16, 0
	s_branch .LBB0_1607
